# prep phase GDN half: loop-invariant conv weights/gate params hoisted, all loads of an iteration issued together (was one wait per load), VOP2 math; sample-unit compute rewritten VOP2
# speedup vs baseline: 1.0738x; 1.0318x over previous
.Lsu_w6:
	s_waitcnt vmcnt(4)
	s_cmpk_gt_i32 s0, 0x7fff
	v_cmp_gt_u32_e32 vcc, 4, v54
	s_cbranch_scc0 .Lsu_rw_fin
	s_add_i32 s2, s0, 0xffff8000
	s_bfe_u32 s1, s2, 0x30005
	s_lshr_b32 s2, s2, 6
	s_and_b32 s4, s2, 0x1fffffc
	s_add_i32 s2, s4, 0x2000
	v_mul_f32_e32 v0, v46, v60
	v_fmac_f32_e32 v0, v47, v61
	v_fmac_f32_e32 v0, v52, v62
	v_fmac_f32_e32 v0, v53, v63
	v_fmac_f32_e32 v0, v48, v56
	v_fmac_f32_e32 v0, v49, v57
	v_fmac_f32_e32 v0, v50, v58
	v_fmac_f32_e32 v0, v51, v59
	v_mul_f32_e64 v45, -v163, v162
	v_mul_f32_e32 v160, v162, v220
	v_add_f32_dpp v0, v0, v0 quad_perm:[1,0,3,2] row_mask:0xf bank_mask:0xf bound_ctrl:1
	v_mul_f32_e32 v46, v163, v46
	v_mul_f32_e32 v47, v163, v47
	v_add_f32_dpp v0, v0, v0 quad_perm:[2,3,0,1] row_mask:0xf bank_mask:0xf bound_ctrl:1
	v_mul_f32_e32 v52, v163, v52
	v_mul_f32_e32 v53, v163, v53
	v_add_f32_dpp v0, v0, v0 row_half_mirror row_mask:0xf bank_mask:0xf bound_ctrl:1
	v_mul_f32_e32 v48, v163, v48
	v_mul_f32_e32 v49, v163, v49
	v_add_f32_dpp v0, v0, v0 row_ror:8 row_mask:0xf bank_mask:0xf bound_ctrl:1
	v_mul_f32_e32 v50, v163, v50
	v_mul_f32_e32 v51, v163, v51
	v_fmac_f32_e32 v160, v45, v0
	v_fmac_f32_e32 v46, v60, v160
	v_fmac_f32_e32 v47, v61, v160
	v_fmac_f32_e32 v52, v62, v160
	v_fmac_f32_e32 v53, v63, v160
	v_fmac_f32_e32 v48, v56, v160
	v_fmac_f32_e32 v49, v57, v160
	v_fmac_f32_e32 v50, v58, v160
	v_fmac_f32_e32 v51, v59, v160
	v_mul_f32_e32 v172, v46, v68
	v_fmac_f32_e32 v172, v47, v69
	v_fmac_f32_e32 v172, v52, v70
	v_fmac_f32_e32 v172, v53, v71
	v_fmac_f32_e32 v172, v48, v64
	v_fmac_f32_e32 v172, v49, v65
	v_fmac_f32_e32 v172, v50, v66
	v_fmac_f32_e32 v172, v51, v67
	v_mul_f32_e32 v0, v46, v76
	v_fmac_f32_e32 v0, v47, v77
	v_add_f32_dpp v172, v172, v172 quad_perm:[1,0,3,2] row_mask:0xf bank_mask:0xf bound_ctrl:1
	v_fmac_f32_e32 v0, v52, v78
	v_fmac_f32_e32 v0, v53, v79
	v_add_f32_dpp v172, v172, v172 quad_perm:[2,3,0,1] row_mask:0xf bank_mask:0xf bound_ctrl:1
	v_fmac_f32_e32 v0, v48, v72
	v_fmac_f32_e32 v0, v49, v73
	v_add_f32_dpp v172, v172, v172 row_half_mirror row_mask:0xf bank_mask:0xf bound_ctrl:1
	v_fmac_f32_e32 v0, v50, v74
	v_fmac_f32_e32 v0, v51, v75
	v_add_f32_dpp v172, v172, v172 row_ror:8 row_mask:0xf bank_mask:0xf bound_ctrl:1
	v_mul_f32_e64 v45, -v165, v164
	v_mul_f32_e32 v160, v164, v55
	v_add_f32_dpp v0, v0, v0 quad_perm:[1,0,3,2] row_mask:0xf bank_mask:0xf bound_ctrl:1
	v_mul_f32_e32 v46, v165, v46
	v_mul_f32_e32 v47, v165, v47
	v_add_f32_dpp v0, v0, v0 quad_perm:[2,3,0,1] row_mask:0xf bank_mask:0xf bound_ctrl:1
	v_mul_f32_e32 v52, v165, v52
	v_mul_f32_e32 v53, v165, v53
	v_add_f32_dpp v0, v0, v0 row_half_mirror row_mask:0xf bank_mask:0xf bound_ctrl:1
	v_mul_f32_e32 v48, v165, v48
	v_mul_f32_e32 v49, v165, v49
	v_add_f32_dpp v0, v0, v0 row_ror:8 row_mask:0xf bank_mask:0xf bound_ctrl:1
	v_mul_f32_e32 v50, v165, v50
	v_mul_f32_e32 v51, v165, v51
	v_fmac_f32_e32 v160, v45, v0
	v_fmac_f32_e32 v46, v76, v160
	v_fmac_f32_e32 v47, v77, v160
	v_fmac_f32_e32 v52, v78, v160
	v_fmac_f32_e32 v53, v79, v160
	v_fmac_f32_e32 v48, v72, v160
	v_fmac_f32_e32 v49, v73, v160
	v_fmac_f32_e32 v50, v74, v160
	v_fmac_f32_e32 v51, v75, v160
	v_mul_f32_e32 v173, v46, v84
	v_fmac_f32_e32 v173, v47, v85
	v_fmac_f32_e32 v173, v52, v86
	v_fmac_f32_e32 v173, v53, v87
	v_fmac_f32_e32 v173, v48, v80
	v_fmac_f32_e32 v173, v49, v81
	v_fmac_f32_e32 v173, v50, v82
	v_fmac_f32_e32 v173, v51, v83
	v_mul_f32_e32 v0, v46, v92
	v_fmac_f32_e32 v0, v47, v93
	v_add_f32_dpp v173, v173, v173 quad_perm:[1,0,3,2] row_mask:0xf bank_mask:0xf bound_ctrl:1
	v_fmac_f32_e32 v0, v52, v94
	v_fmac_f32_e32 v0, v53, v95
	v_add_f32_dpp v173, v173, v173 quad_perm:[2,3,0,1] row_mask:0xf bank_mask:0xf bound_ctrl:1
	v_fmac_f32_e32 v0, v48, v88
	v_fmac_f32_e32 v0, v49, v89
	v_add_f32_dpp v173, v173, v173 row_half_mirror row_mask:0xf bank_mask:0xf bound_ctrl:1
	v_fmac_f32_e32 v0, v50, v90
	v_fmac_f32_e32 v0, v51, v91
	v_add_f32_dpp v173, v173, v173 row_ror:8 row_mask:0xf bank_mask:0xf bound_ctrl:1
	v_mul_f32_e64 v45, -v167, v166
	v_mul_f32_e32 v160, v166, v170
	v_add_f32_dpp v0, v0, v0 quad_perm:[1,0,3,2] row_mask:0xf bank_mask:0xf bound_ctrl:1
	v_mul_f32_e32 v46, v167, v46
	v_mul_f32_e32 v47, v167, v47
	v_add_f32_dpp v0, v0, v0 quad_perm:[2,3,0,1] row_mask:0xf bank_mask:0xf bound_ctrl:1
	v_mul_f32_e32 v52, v167, v52
	v_mul_f32_e32 v53, v167, v53
	v_add_f32_dpp v0, v0, v0 row_half_mirror row_mask:0xf bank_mask:0xf bound_ctrl:1
	v_mul_f32_e32 v48, v167, v48
	v_mul_f32_e32 v49, v167, v49
	v_add_f32_dpp v0, v0, v0 row_ror:8 row_mask:0xf bank_mask:0xf bound_ctrl:1
	v_mul_f32_e32 v50, v167, v50
	v_mul_f32_e32 v51, v167, v51
	v_fmac_f32_e32 v160, v45, v0
	v_fmac_f32_e32 v46, v92, v160
	v_fmac_f32_e32 v47, v93, v160
	v_fmac_f32_e32 v52, v94, v160
	v_fmac_f32_e32 v53, v95, v160
	v_fmac_f32_e32 v48, v88, v160
	v_fmac_f32_e32 v49, v89, v160
	v_fmac_f32_e32 v50, v90, v160
	v_fmac_f32_e32 v51, v91, v160
	v_mul_f32_e32 v174, v46, v100
	v_fmac_f32_e32 v174, v47, v101
	v_fmac_f32_e32 v174, v52, v102
	v_fmac_f32_e32 v174, v53, v103
	v_fmac_f32_e32 v174, v48, v96
	v_fmac_f32_e32 v174, v49, v97
	v_fmac_f32_e32 v174, v50, v98
	v_fmac_f32_e32 v174, v51, v99
	v_mul_f32_e32 v0, v46, v148
	v_fmac_f32_e32 v0, v47, v149
	v_add_f32_dpp v174, v174, v174 quad_perm:[1,0,3,2] row_mask:0xf bank_mask:0xf bound_ctrl:1
	v_fmac_f32_e32 v0, v52, v150
	v_fmac_f32_e32 v0, v53, v151
	v_add_f32_dpp v174, v174, v174 quad_perm:[2,3,0,1] row_mask:0xf bank_mask:0xf bound_ctrl:1
	v_fmac_f32_e32 v0, v48, v116
	v_fmac_f32_e32 v0, v49, v117
	v_add_f32_dpp v174, v174, v174 row_half_mirror row_mask:0xf bank_mask:0xf bound_ctrl:1
	v_fmac_f32_e32 v0, v50, v118
	v_fmac_f32_e32 v0, v51, v119
	v_add_f32_dpp v174, v174, v174 row_ror:8 row_mask:0xf bank_mask:0xf bound_ctrl:1
	v_mul_f32_e64 v45, -v105, v104
	v_mul_f32_e32 v160, v104, v171
	v_add_f32_dpp v0, v0, v0 quad_perm:[1,0,3,2] row_mask:0xf bank_mask:0xf bound_ctrl:1
	v_mul_f32_e32 v46, v105, v46
	v_mul_f32_e32 v47, v105, v47
	v_add_f32_dpp v0, v0, v0 quad_perm:[2,3,0,1] row_mask:0xf bank_mask:0xf bound_ctrl:1
	v_mul_f32_e32 v52, v105, v52
	v_mul_f32_e32 v53, v105, v53
	v_add_f32_dpp v0, v0, v0 row_half_mirror row_mask:0xf bank_mask:0xf bound_ctrl:1
	v_mul_f32_e32 v48, v105, v48
	v_mul_f32_e32 v49, v105, v49
	v_add_f32_dpp v0, v0, v0 row_ror:8 row_mask:0xf bank_mask:0xf bound_ctrl:1
	v_mul_f32_e32 v50, v105, v50
	v_mul_f32_e32 v51, v105, v51
	v_fmac_f32_e32 v160, v45, v0
	v_fmac_f32_e32 v46, v148, v160
	v_fmac_f32_e32 v47, v149, v160
	v_fmac_f32_e32 v52, v150, v160
	v_fmac_f32_e32 v53, v151, v160
	v_fmac_f32_e32 v48, v116, v160
	v_fmac_f32_e32 v49, v117, v160
	v_fmac_f32_e32 v50, v118, v160
	v_fmac_f32_e32 v51, v119, v160
	v_mul_f32_e32 v175, v46, v156
	v_fmac_f32_e32 v175, v47, v157
	v_fmac_f32_e32 v175, v52, v158
	v_fmac_f32_e32 v175, v53, v159
	v_fmac_f32_e32 v175, v48, v152
	v_fmac_f32_e32 v175, v49, v153
	v_fmac_f32_e32 v175, v50, v154
	v_fmac_f32_e32 v175, v51, v155
	v_cmp_eq_u32_e32 vcc, 1, v54
	s_lshl_b32 s1, s1, 7
	v_add_f32_dpp v175, v175, v175 quad_perm:[1,0,3,2] row_mask:0xf bank_mask:0xf bound_ctrl:1
	v_or_b32_e32 v62, s2, v54
	v_mov_b32_e32 v63, v1
	v_add_f32_dpp v175, v175, v175 quad_perm:[2,3,0,1] row_mask:0xf bank_mask:0xf bound_ctrl:1
	v_readlane_b32 s2, v251, 47
	v_readlane_b32 s3, v251, 48
	v_add_f32_dpp v175, v175, v175 row_half_mirror row_mask:0xf bank_mask:0xf bound_ctrl:1
	v_add_u32_e32 v64, s1, v44
	v_lshlrev_b64 v[62:63], 12, v[62:63]
	v_add_f32_dpp v175, v175, v175 row_ror:8 row_mask:0xf bank_mask:0xf bound_ctrl:1
	v_cmp_gt_u32_e64 s[4:5], 4, v54
	v_cndmask_b32_e32 v0, v172, v173, vcc
	v_cmp_eq_u32_e32 vcc, 2, v54
	v_ashrrev_i32_e32 v65, 31, v64
	v_lshl_add_u64 v[62:63], s[2:3], 0, v[62:63]
	v_cndmask_b32_e32 v0, v0, v174, vcc
	v_cmp_eq_u32_e32 vcc, 3, v54
	v_lshl_add_u64 v[62:63], v[64:65], 2, v[62:63]
	v_lshl_add_u64 v[42:43], v[42:43], 2, s[40:41]
	v_cndmask_b32_e32 v0, v0, v175, vcc
	s_and_saveexec_b64 s[24:25], s[4:5]
	global_store_dword v[62:63], v0, off
	s_or_b64 exec, exec, s[24:25]
	global_store_dword v[42:43], v46, off
	global_store_dword v[42:43], v47, off offset:512
	global_store_dword v[42:43], v52, off offset:1024
	global_store_dword v[42:43], v53, off offset:1536
	global_store_dword v[42:43], v48, off offset:2048
	global_store_dword v[42:43], v49, off offset:2560
	global_store_dword v[42:43], v50, off offset:3072
	global_store_dword v[42:43], v51, off offset:3584
	s_add_i32 s13, s13, 1
	s_andn2_b64 vcc, exec, s[94:95]
	s_cbranch_vccnz .LBB0_1789

.Lsu_rw_fin:
	s_ashr_i32 s4, s0, 4
	s_ashr_i32 s1, s0, 6
	s_and_b32 s1, s1, -4
	s_lshl_b32 s0, s4, 6
	s_and_b32 s0, s0, 0x3c0
	s_add_i32 s2, s1, 0x2000
	v_mul_f32_e32 v0, v42, v50
	v_fmac_f32_e32 v0, v43, v51
	v_fmac_f32_e32 v0, v44, v52
	v_fmac_f32_e32 v0, v45, v53
	v_mul_f32_e32 v221, v60, v172
	v_mul_f32_e32 v222, v61, v172
	v_add_f32_dpp v0, v0, v0 quad_perm:[1,0,3,2] row_mask:0xf bank_mask:0xf bound_ctrl:1
	v_mul_f32_e32 v223, v62, v172
	v_mul_f32_e32 v224, v63, v172
	v_add_f32_dpp v0, v0, v0 quad_perm:[2,3,0,1] row_mask:0xf bank_mask:0xf bound_ctrl:1
	v_fmac_f32_e32 v221, v42, v64
	v_fmac_f32_e32 v222, v43, v65
	v_add_f32_dpp v0, v0, v0 row_half_mirror row_mask:0xf bank_mask:0xf bound_ctrl:1
	v_fmac_f32_e32 v223, v44, v66
	v_fmac_f32_e32 v224, v45, v67
	v_add_f32_dpp v0, v0, v0 row_ror:8 row_mask:0xf bank_mask:0xf bound_ctrl:1
	v_fmac_f32_e32 v221, v56, v0
	v_fmac_f32_e32 v222, v57, v0
	v_fmac_f32_e32 v223, v58, v0
	v_fmac_f32_e32 v224, v59, v0
	v_mul_f32_e32 v225, v221, v68
	v_fmac_f32_e32 v225, v222, v69
	v_fmac_f32_e32 v225, v223, v70
	v_fmac_f32_e32 v225, v224, v71
	v_mul_f32_e32 v0, v221, v72
	v_fmac_f32_e32 v0, v222, v73
	v_add_f32_dpp v225, v225, v225 quad_perm:[1,0,3,2] row_mask:0xf bank_mask:0xf bound_ctrl:1
	v_fmac_f32_e32 v0, v223, v74
	v_fmac_f32_e32 v0, v224, v75
	v_add_f32_dpp v225, v225, v225 quad_perm:[2,3,0,1] row_mask:0xf bank_mask:0xf bound_ctrl:1
	v_mul_f32_e32 v42, v80, v174
	v_mul_f32_e32 v43, v81, v174
	v_add_f32_dpp v225, v225, v225 row_half_mirror row_mask:0xf bank_mask:0xf bound_ctrl:1
	v_mul_f32_e32 v44, v82, v174
	v_mul_f32_e32 v45, v83, v174
	v_add_f32_dpp v225, v225, v225 row_ror:8 row_mask:0xf bank_mask:0xf bound_ctrl:1
	v_fmac_f32_e32 v42, v221, v84
	v_fmac_f32_e32 v43, v222, v85
	v_add_f32_dpp v0, v0, v0 quad_perm:[1,0,3,2] row_mask:0xf bank_mask:0xf bound_ctrl:1
	v_fmac_f32_e32 v44, v223, v86
	v_fmac_f32_e32 v45, v224, v87
	v_add_f32_dpp v0, v0, v0 quad_perm:[2,3,0,1] row_mask:0xf bank_mask:0xf bound_ctrl:1
	s_nop 1
	v_add_f32_dpp v0, v0, v0 row_half_mirror row_mask:0xf bank_mask:0xf bound_ctrl:1
	s_nop 1
	v_add_f32_dpp v0, v0, v0 row_ror:8 row_mask:0xf bank_mask:0xf bound_ctrl:1
	v_fmac_f32_e32 v42, v76, v0
	v_fmac_f32_e32 v43, v77, v0
	v_fmac_f32_e32 v44, v78, v0
	v_fmac_f32_e32 v45, v79, v0
	v_mul_f32_e32 v226, v42, v88
	v_fmac_f32_e32 v226, v43, v89
	v_fmac_f32_e32 v226, v44, v90
	v_fmac_f32_e32 v226, v45, v91
	v_mul_f32_e32 v0, v42, v92
	v_fmac_f32_e32 v0, v43, v93
	v_add_f32_dpp v226, v226, v226 quad_perm:[1,0,3,2] row_mask:0xf bank_mask:0xf bound_ctrl:1
	v_fmac_f32_e32 v0, v44, v94
	v_fmac_f32_e32 v0, v45, v95
	v_add_f32_dpp v226, v226, v226 quad_perm:[2,3,0,1] row_mask:0xf bank_mask:0xf bound_ctrl:1
	v_mul_f32_e32 v221, v100, v176
	v_mul_f32_e32 v222, v101, v176
	v_add_f32_dpp v226, v226, v226 row_half_mirror row_mask:0xf bank_mask:0xf bound_ctrl:1
	v_mul_f32_e32 v223, v102, v176
	v_mul_f32_e32 v224, v103, v176
	v_add_f32_dpp v226, v226, v226 row_ror:8 row_mask:0xf bank_mask:0xf bound_ctrl:1
	v_fmac_f32_e32 v221, v42, v116
	v_fmac_f32_e32 v222, v43, v117
	v_add_f32_dpp v0, v0, v0 quad_perm:[1,0,3,2] row_mask:0xf bank_mask:0xf bound_ctrl:1
	v_fmac_f32_e32 v223, v44, v118
	v_fmac_f32_e32 v224, v45, v119
	v_add_f32_dpp v0, v0, v0 quad_perm:[2,3,0,1] row_mask:0xf bank_mask:0xf bound_ctrl:1
	s_nop 1
	v_add_f32_dpp v0, v0, v0 row_half_mirror row_mask:0xf bank_mask:0xf bound_ctrl:1
	s_nop 1
	v_add_f32_dpp v0, v0, v0 row_ror:8 row_mask:0xf bank_mask:0xf bound_ctrl:1
	v_fmac_f32_e32 v221, v96, v0
	v_fmac_f32_e32 v222, v97, v0
	v_fmac_f32_e32 v223, v98, v0
	v_fmac_f32_e32 v224, v99, v0
	v_mul_f32_e32 v227, v221, v148
	v_fmac_f32_e32 v227, v222, v149
	v_fmac_f32_e32 v227, v223, v150
	v_fmac_f32_e32 v227, v224, v151
	v_mul_f32_e32 v0, v221, v152
	v_fmac_f32_e32 v0, v222, v153
	v_add_f32_dpp v227, v227, v227 quad_perm:[1,0,3,2] row_mask:0xf bank_mask:0xf bound_ctrl:1
	v_fmac_f32_e32 v0, v223, v154
	v_fmac_f32_e32 v0, v224, v155
	v_add_f32_dpp v227, v227, v227 quad_perm:[2,3,0,1] row_mask:0xf bank_mask:0xf bound_ctrl:1
	v_mul_f32_e32 v42, v160, v178
	v_mul_f32_e32 v43, v161, v178
	v_add_f32_dpp v227, v227, v227 row_half_mirror row_mask:0xf bank_mask:0xf bound_ctrl:1
	v_mul_f32_e32 v44, v162, v178
	v_mul_f32_e32 v45, v163, v178
	v_add_f32_dpp v227, v227, v227 row_ror:8 row_mask:0xf bank_mask:0xf bound_ctrl:1
	v_fmac_f32_e32 v42, v221, v164
	v_fmac_f32_e32 v43, v222, v165
	v_add_f32_dpp v0, v0, v0 quad_perm:[1,0,3,2] row_mask:0xf bank_mask:0xf bound_ctrl:1
	v_fmac_f32_e32 v44, v223, v166
	v_fmac_f32_e32 v45, v224, v167
	v_add_f32_dpp v0, v0, v0 quad_perm:[2,3,0,1] row_mask:0xf bank_mask:0xf bound_ctrl:1
	s_nop 1
	v_add_f32_dpp v0, v0, v0 row_half_mirror row_mask:0xf bank_mask:0xf bound_ctrl:1
	s_nop 1
	v_add_f32_dpp v0, v0, v0 row_ror:8 row_mask:0xf bank_mask:0xf bound_ctrl:1
	v_fmac_f32_e32 v42, v156, v0
	v_fmac_f32_e32 v43, v157, v0
	v_fmac_f32_e32 v44, v158, v0
	v_fmac_f32_e32 v45, v159, v0
	v_mul_f32_e32 v228, v42, v168
	v_fmac_f32_e32 v228, v43, v169
	v_fmac_f32_e32 v228, v44, v170
	v_fmac_f32_e32 v228, v45, v171
	v_cmp_eq_u32_e32 vcc, 1, v54
	v_add_u32_e32 v58, s0, v48
	v_add_f32_dpp v228, v228, v228 quad_perm:[1,0,3,2] row_mask:0xf bank_mask:0xf bound_ctrl:1
	v_readlane_b32 s0, v251, 37
	v_readlane_b32 s1, v251, 38
	v_add_f32_dpp v228, v228, v228 quad_perm:[2,3,0,1] row_mask:0xf bank_mask:0xf bound_ctrl:1
	v_or_b32_e32 v48, s2, v54
	v_ashrrev_i32_e32 v59, 31, v58
	v_add_f32_dpp v228, v228, v228 row_half_mirror row_mask:0xf bank_mask:0xf bound_ctrl:1
	v_ashrrev_i32_e32 v49, 31, v48
	v_lshl_add_u64 v[46:47], v[46:47], 2, s[22:23]
	v_add_f32_dpp v228, v228, v228 row_ror:8 row_mask:0xf bank_mask:0xf bound_ctrl:1
	v_cmp_gt_u32_e64 s[4:5], 4, v54
	v_cndmask_b32_e32 v0, v225, v226, vcc
	v_cmp_eq_u32_e32 vcc, 2, v54
	v_lshlrev_b64 v[48:49], 12, v[48:49]
	v_lshl_add_u64 v[48:49], s[0:1], 0, v[48:49]
	v_cndmask_b32_e32 v0, v0, v227, vcc
	v_cmp_eq_u32_e32 vcc, 3, v54
	v_lshl_add_u64 v[48:49], v[58:59], 2, v[48:49]
	s_nop 0
	v_cndmask_b32_e32 v0, v0, v228, vcc
	s_and_saveexec_b64 s[24:25], s[4:5]
	global_store_dword v[48:49], v0, off
	s_or_b64 exec, exec, s[24:25]
	global_store_dwordx4 v[46:47], v[42:45], off
	s_add_i32 s13, s13, 1
	s_andn2_b64 vcc, exec, s[94:95]
	s_cbranch_vccnz .LBB0_1789

.LBB0_1878:
	v_readlane_b32 s0, v251, 29
	v_readlane_b32 s1, v251, 30
	s_mov_b32 s2, s0
	s_mul_hi_i32 s9, s0, 0x120000
	v_readlane_b32 s0, v251, 23
	s_cmp_gt_i32 s0, 0x87ff
	s_mul_i32 s8, s2, 0x120000
	v_readlane_b32 s1, v251, 24
	s_cbranch_scc1 .LBB0_1931
	v_readlane_b32 s0, v251, 29
	v_readlane_b32 s1, v251, 30
	s_mul_i32 s2, s0, 0x3000
	s_lshl_b32 s4, s0, 3
	s_ashr_i32 s3, s2, 31
	s_ashr_i32 s5, s4, 31
	s_lshl_b64 s[0:1], s[8:9], 2
	s_waitcnt lgkmcnt(0)
	s_add_u32 s0, s16, s0
	s_addc_u32 s1, s17, s1
	s_lshl_b64 s[2:3], s[2:3], 2
	s_add_u32 s10, s22, s2
	s_addc_u32 s11, s23, s3
	s_lshl_b64 s[2:3], s[4:5], 2
	s_add_u32 s12, s24, s2
	s_addc_u32 s13, s25, s3
	s_add_u32 s16, s28, s2
	s_addc_u32 s17, s29, s3
	v_readlane_b32 s2, v251, 1
	v_readlane_b32 s3, v251, 2
	s_add_u32 s22, s2, 0x2c900000
	s_addc_u32 s23, s3, 0
	s_add_u32 s24, s2, 0x2eb00000
	s_addc_u32 s25, s3, 0
	s_add_u32 s28, s2, 0x30d00000
	s_addc_u32 s29, s3, 0
	s_add_u32 s4, s2, 0x32f00000
	s_addc_u32 s5, s3, 0
	s_add_u32 s30, s10, 0x3000
	s_addc_u32 s31, s11, 0
	s_add_u32 s34, s10, 0x6000
	s_addc_u32 s35, s11, 0
	s_waitcnt vmcnt(0)
	v_and_b32_e32 v4, 64, v206
	s_add_u32 s36, s10, 0x9000
	v_xor_b32_e32 v3, 16, v206
	v_add_u32_e32 v4, 64, v4
	v_readlane_b32 s6, v251, 0
	s_addc_u32 s37, s11, 0
	v_cmp_lt_i32_e32 vcc, v3, v4
	s_lshl_b32 s6, s6, 1
	v_readlane_b32 s7, v252, 51
	v_and_b32_e32 v2, 31, v219
	v_cndmask_b32_e32 v3, v206, v3, vcc
	s_add_i32 s18, s7, s6
	v_readlane_b32 s6, v251, 23
	v_lshrrev_b32_e32 v0, 5, v138
	v_lshlrev_b32_e32 v72, 2, v2
	v_lshlrev_b32_e32 v73, 2, v3
	v_cmp_eq_u32_e64 s[2:3], 0, v2
	s_mov_b32 s19, s6
	v_readlane_b32 s7, v251, 24
	v_and_or_b32 v84, s18, 6, v0
	v_mov_b32_e32 v191, 0xffff0000
	v_lshl_or_b32 v85, v84, 7, v72
	v_lshlrev_b32_e32 v192, 3, v84
	v_lshlrev_b32_e32 v193, 2, v84
	v_lshlrev_b32_e32 v86, 2, v85
	v_lshlrev_b32_e32 v89, 1, v85
	v_lshlrev_b32_e32 v190, 1, v84
	v_add_u32_e32 v87, 0x1000, v86
	v_add_u32_e32 v88, 0x2000, v86
	v_add_u32_e32 v90, 0x800, v89
	v_add_u32_e32 v91, 0x1000, v89
	v_add_u32_e32 v190, 0x2000, v190
	global_load_dword v188, v193, s[12:13]
	global_load_dword v189, v193, s[16:17]
	global_load_dwordx4 v[140:143], v86, s[10:11]
	global_load_dwordx4 v[144:147], v87, s[10:11]
	global_load_dwordx4 v[148:151], v88, s[10:11]
	global_load_dwordx4 v[152:155], v86, s[30:31]
	global_load_dwordx4 v[156:159], v87, s[30:31]
	global_load_dwordx4 v[160:163], v88, s[30:31]
	global_load_dwordx4 v[164:167], v86, s[34:35]
	global_load_dwordx4 v[168:171], v87, s[34:35]
	global_load_dwordx4 v[172:175], v88, s[34:35]
	global_load_dwordx4 v[176:179], v86, s[36:37]
	global_load_dwordx4 v[180:183], v87, s[36:37]
	global_load_dwordx4 v[184:187], v88, s[36:37]
	s_waitcnt vmcnt(0)
	v_mul_f32_e32 v188, 0x3fb8aa3b, v188
	v_exp_f32_e32 v188, v188
	s_branch .LBB0_1881

.LBB0_1881:
	s_ashr_i32 s40, s19, 2
	s_and_b32 s6, s40, 0x7ff
	s_cmpk_gt_i32 s40, 0x1fff
	s_cbranch_scc1 .Lgdp_slow
	s_cmp_lt_u32 s6, 3
	s_cbranch_scc1 .Lgdp_slow
	s_add_i32 s6, s40, -3
	v_readlane_b32 s48, v251, 16
	v_readlane_b32 s49, v251, 17
	s_mul_hi_i32 s7, s6, 0x3c00
	s_mulk_i32 s6, 0x3c00
	s_add_u32 s6, s48, s6
	s_addc_u32 s7, s49, s7
	s_add_u32 s6, s6, 0x1a00
	s_addc_u32 s7, s7, 0
	s_add_u32 s26, s6, 0x3c00
	s_addc_u32 s27, s7, 0
	s_add_u32 s38, s26, 0x3c00
	s_addc_u32 s39, s27, 0
	s_add_u32 s42, s38, 0x3c00
	s_addc_u32 s43, s39, 0
	global_load_dwordx2 v[2:3], v89, s[6:7]
	global_load_dwordx2 v[4:5], v90, s[6:7]
	global_load_dwordx2 v[6:7], v91, s[6:7]
	global_load_dwordx2 v[8:9], v89, s[26:27]
	global_load_dwordx2 v[10:11], v90, s[26:27]
	global_load_dwordx2 v[12:13], v91, s[26:27]
	global_load_dwordx2 v[14:15], v89, s[38:39]
	global_load_dwordx2 v[16:17], v90, s[38:39]
	global_load_dwordx2 v[18:19], v91, s[38:39]
	global_load_dwordx2 v[20:21], v89, s[42:43]
	global_load_dwordx2 v[22:23], v90, s[42:43]
	global_load_dwordx2 v[24:25], v91, s[42:43]
	global_load_ushort v26, v190, s[42:43]
	global_load_ushort v27, v190, s[42:43] offset:16
	s_lshl_b32 s44, s40, 12
	v_add_u32_e32 v56, s44, v86
	s_waitcnt vmcnt(0)
	v_lshlrev_b32_e32 v40, 16, v2
	v_and_b32_e32 v41, v191, v2
	v_lshlrev_b32_e32 v42, 16, v3
	v_and_b32_e32 v43, v191, v3
	v_mul_f32_e32 v28, v40, v140
	v_mul_f32_e32 v29, v41, v141
	v_mul_f32_e32 v30, v42, v142
	v_mul_f32_e32 v31, v43, v143
	v_lshlrev_b32_e32 v40, 16, v8
	v_and_b32_e32 v41, v191, v8
	v_lshlrev_b32_e32 v42, 16, v9
	v_and_b32_e32 v43, v191, v9
	v_fmac_f32_e32 v28, v40, v152
	v_fmac_f32_e32 v29, v41, v153
	v_fmac_f32_e32 v30, v42, v154
	v_fmac_f32_e32 v31, v43, v155
	v_lshlrev_b32_e32 v40, 16, v14
	v_and_b32_e32 v41, v191, v14
	v_lshlrev_b32_e32 v42, 16, v15
	v_and_b32_e32 v43, v191, v15
	v_fmac_f32_e32 v28, v40, v164
	v_fmac_f32_e32 v29, v41, v165
	v_fmac_f32_e32 v30, v42, v166
	v_fmac_f32_e32 v31, v43, v167
	v_lshlrev_b32_e32 v40, 16, v20
	v_and_b32_e32 v41, v191, v20
	v_lshlrev_b32_e32 v42, 16, v21
	v_and_b32_e32 v43, v191, v21
	v_fmac_f32_e32 v28, v40, v176
	v_fmac_f32_e32 v29, v41, v177
	v_fmac_f32_e32 v30, v42, v178
	v_fmac_f32_e32 v31, v43, v179
	v_lshlrev_b32_e32 v40, 16, v4
	v_and_b32_e32 v41, v191, v4
	v_lshlrev_b32_e32 v42, 16, v5
	v_and_b32_e32 v43, v191, v5
	v_mul_f32_e32 v32, v40, v144
	v_mul_f32_e32 v33, v41, v145
	v_mul_f32_e32 v34, v42, v146
	v_mul_f32_e32 v35, v43, v147
	v_lshlrev_b32_e32 v40, 16, v10
	v_and_b32_e32 v41, v191, v10
	v_lshlrev_b32_e32 v42, 16, v11
	v_and_b32_e32 v43, v191, v11
	v_fmac_f32_e32 v32, v40, v156
	v_fmac_f32_e32 v33, v41, v157
	v_fmac_f32_e32 v34, v42, v158
	v_fmac_f32_e32 v35, v43, v159
	v_lshlrev_b32_e32 v40, 16, v16
	v_and_b32_e32 v41, v191, v16
	v_lshlrev_b32_e32 v42, 16, v17
	v_and_b32_e32 v43, v191, v17
	v_fmac_f32_e32 v32, v40, v168
	v_fmac_f32_e32 v33, v41, v169
	v_fmac_f32_e32 v34, v42, v170
	v_fmac_f32_e32 v35, v43, v171
	v_lshlrev_b32_e32 v40, 16, v22
	v_and_b32_e32 v41, v191, v22
	v_lshlrev_b32_e32 v42, 16, v23
	v_and_b32_e32 v43, v191, v23
	v_fmac_f32_e32 v32, v40, v180
	v_fmac_f32_e32 v33, v41, v181
	v_fmac_f32_e32 v34, v42, v182
	v_fmac_f32_e32 v35, v43, v183
	v_lshlrev_b32_e32 v40, 16, v6
	v_and_b32_e32 v41, v191, v6
	v_lshlrev_b32_e32 v42, 16, v7
	v_and_b32_e32 v43, v191, v7
	v_mul_f32_e32 v36, v40, v148
	v_mul_f32_e32 v37, v41, v149
	v_mul_f32_e32 v38, v42, v150
	v_mul_f32_e32 v39, v43, v151
	v_lshlrev_b32_e32 v40, 16, v12
	v_and_b32_e32 v41, v191, v12
	v_lshlrev_b32_e32 v42, 16, v13
	v_and_b32_e32 v43, v191, v13
	v_fmac_f32_e32 v36, v40, v160
	v_fmac_f32_e32 v37, v41, v161
	v_fmac_f32_e32 v38, v42, v162
	v_fmac_f32_e32 v39, v43, v163
	v_lshlrev_b32_e32 v40, 16, v18
	v_and_b32_e32 v41, v191, v18
	v_lshlrev_b32_e32 v42, 16, v19
	v_and_b32_e32 v43, v191, v19
	v_fmac_f32_e32 v36, v40, v172
	v_fmac_f32_e32 v37, v41, v173
	v_fmac_f32_e32 v38, v42, v174
	v_fmac_f32_e32 v39, v43, v175
	v_lshlrev_b32_e32 v40, 16, v24
	v_and_b32_e32 v41, v191, v24
	v_lshlrev_b32_e32 v42, 16, v25
	v_and_b32_e32 v43, v191, v25
	v_fmac_f32_e32 v36, v40, v184
	v_fmac_f32_e32 v37, v41, v185
	v_fmac_f32_e32 v38, v42, v186
	v_fmac_f32_e32 v39, v43, v187
	v_mul_f32_e32 v44, s81, v28
	v_mul_f32_e32 v45, s81, v29
	v_mul_f32_e32 v46, s81, v30
	v_mul_f32_e32 v47, s81, v31
	v_mul_f32_e32 v48, s81, v32
	v_mul_f32_e32 v49, s81, v33
	v_mul_f32_e32 v50, s81, v34
	v_mul_f32_e32 v51, s81, v35
	v_mul_f32_e32 v52, s81, v36
	v_mul_f32_e32 v53, s81, v37
	v_mul_f32_e32 v54, s81, v38
	v_mul_f32_e32 v55, s81, v39
	v_exp_f32_e32 v44, v44
	v_exp_f32_e32 v45, v45
	v_exp_f32_e32 v46, v46
	v_exp_f32_e32 v47, v47
	v_exp_f32_e32 v48, v48
	v_exp_f32_e32 v49, v49
	v_exp_f32_e32 v50, v50
	v_exp_f32_e32 v51, v51
	v_exp_f32_e32 v52, v52
	v_exp_f32_e32 v53, v53
	v_exp_f32_e32 v54, v54
	v_exp_f32_e32 v55, v55
	v_add_f32_e32 v44, 1.0, v44
	v_add_f32_e32 v45, 1.0, v45
	v_add_f32_e32 v46, 1.0, v46
	v_add_f32_e32 v47, 1.0, v47
	v_add_f32_e32 v48, 1.0, v48
	v_add_f32_e32 v49, 1.0, v49
	v_add_f32_e32 v50, 1.0, v50
	v_add_f32_e32 v51, 1.0, v51
	v_add_f32_e32 v52, 1.0, v52
	v_add_f32_e32 v53, 1.0, v53
	v_add_f32_e32 v54, 1.0, v54
	v_add_f32_e32 v55, 1.0, v55
	v_rcp_f32_e32 v44, v44
	v_rcp_f32_e32 v45, v45
	v_rcp_f32_e32 v46, v46
	v_rcp_f32_e32 v47, v47
	v_rcp_f32_e32 v48, v48
	v_rcp_f32_e32 v49, v49
	v_rcp_f32_e32 v50, v50
	v_rcp_f32_e32 v51, v51
	v_rcp_f32_e32 v52, v52
	v_rcp_f32_e32 v53, v53
	v_rcp_f32_e32 v54, v54
	v_rcp_f32_e32 v55, v55
	v_mul_f32_e32 v28, v28, v44
	v_mul_f32_e32 v29, v29, v45
	v_mul_f32_e32 v30, v30, v46
	v_mul_f32_e32 v31, v31, v47
	v_mul_f32_e32 v32, v32, v48
	v_mul_f32_e32 v33, v33, v49
	v_mul_f32_e32 v34, v34, v50
	v_mul_f32_e32 v35, v35, v51
	v_mul_f32_e32 v36, v36, v52
	v_mul_f32_e32 v37, v37, v53
	v_mul_f32_e32 v38, v38, v54
	v_mul_f32_e32 v39, v39, v55
	v_mul_f32_e32 v44, v28, v28
	v_mul_f32_e32 v45, v32, v32
	v_mul_f32_e32 v46, v29, v29
	v_mul_f32_e32 v47, v33, v33
	v_fmac_f32_e32 v44, v30, v30
	v_fmac_f32_e32 v45, v34, v34
	v_fmac_f32_e32 v46, v31, v31
	v_fmac_f32_e32 v47, v35, v35
	v_add_f32_e32 v44, v44, v46
	v_add_f32_e32 v45, v45, v47
	s_nop 0
	v_add_f32_dpp v44, v44, v44 quad_perm:[1,0,3,2] row_mask:0xf bank_mask:0xf bound_ctrl:1
	v_add_f32_dpp v45, v45, v45 quad_perm:[1,0,3,2] row_mask:0xf bank_mask:0xf bound_ctrl:1
	s_nop 0
	v_add_f32_dpp v44, v44, v44 quad_perm:[2,3,0,1] row_mask:0xf bank_mask:0xf bound_ctrl:1
	v_add_f32_dpp v45, v45, v45 quad_perm:[2,3,0,1] row_mask:0xf bank_mask:0xf bound_ctrl:1
	s_nop 0
	v_add_f32_dpp v44, v44, v44 row_half_mirror row_mask:0xf bank_mask:0xf bound_ctrl:1
	v_add_f32_dpp v45, v45, v45 row_half_mirror row_mask:0xf bank_mask:0xf bound_ctrl:1
	s_nop 0
	v_add_f32_dpp v44, v44, v44 row_ror:8 row_mask:0xf bank_mask:0xf bound_ctrl:1
	v_add_f32_dpp v45, v45, v45 row_ror:8 row_mask:0xf bank_mask:0xf bound_ctrl:1
	s_nop 0
	ds_bpermute_b32 v46, v73, v44
	ds_bpermute_b32 v47, v73, v45
	s_add_u32 s26, s4, s44
	s_addc_u32 s27, s5, 0
	s_waitcnt lgkmcnt(0)
	v_add_f32_e32 v44, v44, v46
	v_add_f32_e32 v45, v45, v47
	v_add_f32_e32 v44, 0x2b8cbccc, v44
	v_add_f32_e32 v45, 0x2b8cbccc, v45
	v_rsq_f32_e32 v44, v44
	v_rsq_f32_e32 v45, v45
	s_nop 0
	v_mul_f32_e32 v44, 0x3db504f3, v44
	v_mul_f32_e32 v28, v28, v44
	v_mul_f32_e32 v29, v29, v44
	v_mul_f32_e32 v30, v30, v44
	v_mul_f32_e32 v31, v31, v44
	v_mul_f32_e32 v32, v32, v45
	v_mul_f32_e32 v33, v33, v45
	v_mul_f32_e32 v34, v34, v45
	v_mul_f32_e32 v35, v35, v45
	global_store_dwordx4 v56, v[28:31], s[22:23]
	global_store_dwordx4 v56, v[32:35], s[24:25]
	global_store_dwordx4 v56, v[36:39], s[28:29]
	s_and_saveexec_b64 s[38:39], s[2:3]
	v_lshlrev_b32_e32 v44, 16, v26
	v_lshlrev_b32_e32 v45, 16, v27
	v_mul_f32_e32 v44, s81, v44
	v_add_f32_e32 v45, v189, v45
	v_exp_f32_e32 v44, v44
	v_mul_f32_e64 v46, |v45|, s81
	v_exp_f32_e32 v46, v46
	v_add_f32_e32 v44, 1.0, v44
	v_rcp_f32_e32 v44, v44
	v_max_f32_e32 v45, 0, v45
	v_add_f32_e32 v46, 1.0, v46
	global_store_dword v192, v44, s[26:27]
	v_cmp_gt_f32_e32 vcc, s82, v46
	s_nop 1
	v_cndmask_b32_e64 v47, 0, 32, vcc
	v_ldexp_f32 v46, v46, v47
	v_log_f32_e32 v46, v46
	s_nop 0
	v_mul_f32_e32 v47, 0x3f317217, v46
	v_fma_f32 v47, v46, s83, -v47
	v_fmac_f32_e32 v47, 0x3377d1cf, v46
	v_fmac_f32_e32 v47, 0x3f317217, v46
	v_cmp_lt_f32_e64 s[6:7], |v46|, s84
	s_nop 1
	v_cndmask_b32_e64 v46, v46, v47, s[6:7]
	v_cndmask_b32_e32 v47, 0, v218, vcc
	v_sub_f32_e32 v46, v46, v47
	v_add_f32_e32 v45, v45, v46
	v_mul_f32_e32 v45, v45, v188
	v_mul_f32_e32 v45, s81, v45
	v_exp_f32_e32 v45, v45
	s_nop 0
	global_store_dword v192, v45, s[26:27] offset:4
	s_or_b64 exec, exec, s[38:39]
	s_add_i32 s19, s19, s50
	s_add_i32 s18, s18, s80
	s_cmp_gt_i32 s19, 0x87ff
	s_cbranch_scc0 .LBB0_1881
	s_branch .LBB0_1931
.Lgdp_slow:
	s_cmpk_gt_i32 s40, 0x1fff
	s_mov_b64 s[6:7], -1
	s_cbranch_scc0 .LBB0_1883
	s_add_i32 s6, s40, 0xffffe000
	s_lshr_b32 s6, s6, 2
	s_bfe_u32 s26, s19, 0x20002
	s_and_b32 s27, s40, 0x7ffffffc
	s_mul_i32 s7, s6, 3
	s_mul_i32 s6, s6, 0x9000
	s_mul_hi_u32 s7, s7, 0x3000
	s_add_u32 s38, s0, s6
	s_addc_u32 s39, s1, s7
	s_mov_b64 s[6:7], 0
